# m1 chunk prologue: V^T staging and conv loads hoisted above the wave-0 gate preamble, single wait (on top of the same restructure in m3)
# speedup vs baseline: 1.0216x; 1.0028x over previous
.LBB0_288:
	s_ashr_i32 s4, s26, 10
	s_and_b32 s28, s26, 0x7f
	s_ashr_i32 s5, s4, 31
	v_mov_b32_e32 v15, v194
	s_lshl_b64 s[20:21], s[4:5], 13
	s_lshl_b32 s4, s28, 6
	s_bfe_u32 s29, s26, 0x30007
	v_and_b32_e32 v14, 63, v15
	v_readfirstlane_b32 s27, v15
	s_or_b32 s20, s20, s4
	v_lshrrev_b32_e32 v209, 3, v15
	v_and_b32_e32 v210, 7, v15
	v_lshlrev_b32_e32 v211, 4, v210
	v_lshl_or_b32 v190, v209, 15, v211
	v_lshl_or_b32 v192, v209, 11, v211
	v_add_u32_e32 v193, 0x1000, v192
	v_lshlrev_b32_e32 v208, 5, v210
	s_lshl_b32 s90, s29, 7
	s_or_b32 s90, s90, 0x400
	s_lshl_b64 s[52:53], s[20:21], 1
	s_add_u32 s52, s22, s52
	s_addc_u32 s53, s23, s53
	s_lshl_b32 s91, s90, 15
	s_add_u32 s52, s52, s91
	s_addc_u32 s53, s53, 0
	s_add_u32 s54, s52, 0x200000
	s_addc_u32 s55, s53, 0
	global_load_dwordx4 v[44:47], v190, s[52:53]
	global_load_dwordx4 v[48:51], v190, s[54:55]
	s_lshl_b32 s91, s29, 8
	s_add_u32 s94, s8, s91
	s_addc_u32 s95, s9, 0
	global_load_dwordx4 v[72:75], v208, s[94:95] offset:2048
	global_load_dwordx4 v[76:79], v208, s[94:95] offset:2064
	s_add_u32 s94, s2, s91
	s_addc_u32 s95, s3, 0
	global_load_dwordx4 v[84:87], v208, s[94:95] offset:2048
	global_load_dwordx4 v[88:91], v208, s[94:95] offset:2064
	s_add_u32 s94, s94, 0x1000
	s_addc_u32 s95, s95, 0
	global_load_dwordx4 v[96:99], v208, s[94:95] offset:2048
	global_load_dwordx4 v[100:103], v208, s[94:95] offset:2064
	s_add_u32 s94, s94, 0x1000
	s_addc_u32 s95, s95, 0
	global_load_dwordx4 v[108:111], v208, s[94:95] offset:2048
	global_load_dwordx4 v[112:115], v208, s[94:95] offset:2064
	s_add_u32 s94, s94, 0x1000
	s_addc_u32 s95, s95, 0
	global_load_dwordx4 v[120:123], v208, s[94:95] offset:2048
	global_load_dwordx4 v[124:127], v208, s[94:95] offset:2064
	s_sub_u32 s92, s20, 3
	s_subb_u32 s93, s21, 0
	s_lshl_b64 s[92:93], s[92:93], 11
	s_add_u32 s92, s0, s92
	s_addc_u32 s93, s1, s93
	s_lshl_b32 s91, s29, 7
	s_add_u32 s92, s92, s91
	s_addc_u32 s93, s93, 0
	s_cmp_lg_u32 s28, 0
	s_cselect_b64 s[54:55], -1, 0
	v_cmp_lt_u32_e32 vcc, 2, v209
	s_or_b64 s[46:47], s[54:55], vcc
	v_cmp_lt_u32_e32 vcc, 1, v209
	s_or_b64 s[48:49], s[54:55], vcc
	v_cmp_lt_u32_e32 vcc, 0, v209
	s_or_b64 s[50:51], s[54:55], vcc
	s_mov_b64 s[96:97], exec
	s_and_b64 exec, s[96:97], s[46:47]
	global_load_dwordx4 v[80:83], v192, s[92:93] offset:1024
	s_and_b64 exec, s[96:97], s[48:49]
	global_load_dwordx4 v[92:95], v192, s[92:93] offset:3072
	s_and_b64 exec, s[96:97], s[50:51]
	global_load_dwordx4 v[104:107], v193, s[92:93] offset:1024
	s_mov_b64 exec, s[96:97]
	global_load_dwordx4 v[116:119], v193, s[92:93] offset:3072
	s_cmp_gt_u32 s27, 63
	v_cmp_gt_u32_e32 vcc, 16, v14
	s_cbranch_scc1 .LBB0_292
	v_or_b32_e32 v0, s20, v14
	v_mov_b32_e32 v1, s21
	v_lshlrev_b64 v[0:1], 6, v[0:1]
	v_lshl_add_u64 v[0:1], s[14:15], 0, v[0:1]
	s_lshl_b32 s86, s29, 2
	v_lshl_add_u64 v[0:1], v[0:1], 0, s[86:87]
	v_mov_b32_e32 v3, s86
	global_load_dword v2, v[0:1], off offset:32
	global_load_dword v4, v3, s[10:11]
	s_nop 0
	global_load_dword v0, v[0:1], off
	s_nop 0
	global_load_dword v1, v3, s[12:13]
	s_waitcnt vmcnt(2)
	v_add_f32_e32 v2, v2, v4
	s_waitcnt vmcnt(0)
	v_add_f32_e32 v0, v0, v1
	v_min_f32_e32 v1, 0, v2
	v_mul_f32_e64 v2, |v2|, s79
	v_exp_f32_e32 v4, v2
	s_nop 0
	v_add_f32_e32 v5, 1.0, v4
	v_add_f32_e32 v2, -1.0, v5
	v_sub_f32_e32 v3, v2, v5
	v_add_f32_e32 v3, 1.0, v3
	v_sub_f32_e32 v2, v4, v2
	v_add_f32_e32 v6, v2, v3
	v_frexp_mant_f32_e32 v2, v5
	v_cmp_gt_f32_e64 s[4:5], s85, v2
	v_cvt_f64_f32_e32 v[2:3], v5
	v_frexp_exp_i32_f64_e32 v2, v[2:3]
	v_subbrev_co_u32_e64 v2, s[4:5], 0, v2, s[4:5]
	v_sub_u32_e32 v3, 0, v2
	v_ldexp_f32 v5, v5, v3
	v_ldexp_f32 v3, v6, v3
	v_add_f32_e32 v6, -1.0, v5
	v_add_f32_e32 v7, 1.0, v6
	v_sub_f32_e32 v7, v5, v7
	v_add_f32_e32 v7, v3, v7
	v_add_f32_e32 v8, v6, v7
	v_sub_f32_e32 v6, v8, v6
	v_sub_f32_e32 v6, v7, v6
	v_add_f32_e32 v7, 1.0, v5
	v_add_f32_e32 v9, -1.0, v7
	v_sub_f32_e32 v5, v5, v9
	v_add_f32_e32 v3, v3, v5
	v_add_f32_e32 v5, v7, v3
	v_sub_f32_e32 v7, v5, v7
	v_sub_f32_e32 v3, v3, v7
	v_rcp_f32_e32 v7, v5
	v_cvt_f32_i32_e32 v2, v2
	s_mov_b32 s4, 0x3f317218
	v_mul_f32_e32 v9, v8, v7
	v_mul_f32_e32 v10, v5, v9
	v_fma_f32 v11, v9, v5, -v10
	v_fmac_f32_e32 v11, v9, v3
	v_add_f32_e32 v12, v10, v11
	v_sub_f32_e32 v13, v8, v12
	v_sub_f32_e32 v8, v8, v13
	v_sub_f32_e32 v10, v12, v10
	v_sub_f32_e32 v8, v8, v12
	v_add_f32_e32 v6, v6, v8
	v_sub_f32_e32 v8, v10, v11
	v_add_f32_e32 v6, v8, v6
	v_add_f32_e32 v8, v13, v6
	v_mul_f32_e32 v10, v7, v8
	v_mul_f32_e32 v11, v5, v10
	v_fma_f32 v5, v10, v5, -v11
	v_fmac_f32_e32 v5, v10, v3
	v_sub_f32_e32 v3, v13, v8
	v_add_f32_e32 v3, v6, v3
	v_add_f32_e32 v6, v11, v5
	v_sub_f32_e32 v12, v8, v6
	v_sub_f32_e32 v8, v8, v12
	v_sub_f32_e32 v11, v6, v11
	v_sub_f32_e32 v6, v8, v6
	v_add_f32_e32 v3, v3, v6
	v_sub_f32_e32 v5, v11, v5
	v_add_f32_e32 v3, v5, v3
	v_add_f32_e32 v5, v9, v10
	v_add_f32_e32 v3, v12, v3
	v_sub_f32_e32 v6, v5, v9
	v_mul_f32_e32 v3, v7, v3
	v_sub_f32_e32 v6, v10, v6
	v_add_f32_e32 v3, v6, v3
	v_mul_f32_e32 v9, 0x3f317218, v2
	v_add_f32_e32 v6, v5, v3
	v_fma_f32 v10, v2, s4, -v9
	v_mul_f32_e32 v7, v6, v6
	v_fmac_f32_e32 v10, 0xb102e308, v2
	v_sub_f32_e32 v2, v6, v5
	v_fmamk_f32 v8, v7, 0x3e9b6dac, v200
	v_sub_f32_e32 v2, v3, v2
	v_add_f32_e32 v3, v9, v10
	v_fmaak_f32 v8, v7, v8, 0x3f2aaada
	v_sub_f32_e32 v5, v3, v9
	v_ldexp_f32 v9, v6, 1
	v_mul_f32_e32 v6, v6, v7
	v_mul_f32_e32 v6, v6, v8
	v_add_f32_e32 v7, v9, v6
	v_sub_f32_e32 v8, v7, v9
	v_ldexp_f32 v2, v2, 1
	v_sub_f32_e32 v6, v6, v8
	v_add_f32_e32 v2, v2, v6
	v_add_f32_e32 v6, v7, v2
	v_sub_f32_e32 v7, v6, v7
	v_sub_f32_e32 v2, v2, v7
	v_add_f32_e32 v7, v3, v6
	v_sub_f32_e32 v8, v7, v3
	v_sub_f32_e32 v9, v7, v8
	v_sub_f32_e32 v5, v10, v5
	v_sub_f32_e32 v3, v3, v9
	v_sub_f32_e32 v6, v6, v8
	v_add_f32_e32 v3, v6, v3
	v_add_f32_e32 v6, v5, v2
	v_sub_f32_e32 v8, v6, v5
	v_sub_f32_e32 v9, v6, v8
	v_sub_f32_e32 v5, v5, v9
	v_sub_f32_e32 v2, v2, v8
	v_add_f32_e32 v3, v6, v3
	v_add_f32_e32 v2, v2, v5
	v_add_f32_e32 v5, v7, v3
	v_sub_f32_e32 v6, v5, v7
	v_sub_f32_e32 v3, v3, v6
	v_add_f32_e32 v2, v2, v3
	s_mov_b32 s4, 0x7f800000
	v_add_f32_e32 v2, v5, v2
	v_cmp_neq_f32_e64 s[4:5], s4, v4
	v_add_u32_e32 v3, -1, v201
	s_nop 0
	v_cndmask_b32_e64 v2, v202, v2, s[4:5]
	v_cmp_ngt_f32_e64 s[4:5], -1.0, v4
	s_nop 1
	v_cndmask_b32_e64 v2, v203, v2, s[4:5]
	v_cmp_neq_f32_e64 s[4:5], -1.0, v4
	s_nop 1
	v_cndmask_b32_e64 v2, v204, v2, s[4:5]
	s_mov_b32 s4, 0x33800000
	v_cmp_lt_f32_e64 s[4:5], |v4|, s4
	s_nop 1
	v_cndmask_b32_e64 v2, v2, v4, s[4:5]
	v_sub_f32_e32 v1, v1, v2
	v_mov_b32_e32 v4, v1
	s_nop 1
	v_add_f32_dpp v4, v1, v4 row_shr:1 row_mask:0xf bank_mask:0xf
	v_add_f32_dpp v4, v1, v4 row_shr:2 row_mask:0xf bank_mask:0xf
	v_add_f32_dpp v4, v1, v4 row_shr:3 row_mask:0xf bank_mask:0xf
	s_nop 1
	v_add_f32_dpp v4, v4, v4 row_shr:4 row_mask:0xf bank_mask:0xe
	s_nop 1
	v_add_f32_dpp v4, v4, v4 row_shr:8 row_mask:0xf bank_mask:0xc
	s_nop 1
	v_add_f32_dpp v4, v4, v4 row_bcast:15 row_mask:0xa bank_mask:0xf
	s_nop 1
	v_add_f32_dpp v4, v4, v4 row_bcast:31 row_mask:0xc bank_mask:0xf
	s_nop 0
	v_readlane_b32 s6, v4, 63
	s_nop 1
	v_mov_b32_e32 v1, s6
	v_sub_f32_e32 v2, v1, v4
	v_add_f32_e32 v2, v0, v2
	v_mov_b32_e32 v3, v2
	s_nop 1
	v_max_f32_dpp v3, v2, v3 row_shr:1 row_mask:0xf bank_mask:0xf
	v_max_f32_dpp v3, v2, v3 row_shr:2 row_mask:0xf bank_mask:0xf
	v_max_f32_dpp v3, v2, v3 row_shr:3 row_mask:0xf bank_mask:0xf
	s_nop 1
	v_max_f32_dpp v3, v3, v3 row_shr:4 row_mask:0xf bank_mask:0xe
	s_nop 1
	v_max_f32_dpp v3, v3, v3 row_shr:8 row_mask:0xf bank_mask:0xc
	s_nop 1
	v_max_f32_dpp v3, v3, v3 row_bcast:15 row_mask:0xa bank_mask:0xf
	s_nop 1
	v_max_f32_dpp v3, v3, v3 row_bcast:31 row_mask:0xc bank_mask:0xf
	s_nop 0
	v_readlane_b32 s7, v3, 63
	v_cmp_eq_u32_e64 s[4:5], 0, v14
	s_nop 1
	v_mov_b32_e32 v0, s7
	v_sub_f32_e32 v2, v2, v0
	v_mul_f32_e32 v2, 0x3fb8aa3b, v2
	v_exp_f32_e32 v2, v2
	v_lshl_add_u32 v3, v14, 2, 0
	ds_write_b32 v3, v2 offset:29952
	s_and_saveexec_b64 s[6:7], s[4:5]
	s_cbranch_execz .LBB0_291
	s_ashr_i32 s19, s18, 31
	s_lshl_b64 s[4:5], s[18:19], 2
	s_add_u32 s4, s24, s4
	s_addc_u32 s5, s25, s5
	global_store_dwordx2 v172, v[0:1], s[4:5]

.LBB0_292:
	v_lshrrev_b32_e32 v8, 3, v15
	v_and_b32_e32 v16, 7, v15
	v_lshlrev_b32_e32 v16, 3, v16
	v_mul_u32_u24_e32 v24, 0x90, v8
	v_lshl_add_u32 v24, v16, 1, v24
	s_waitcnt vmcnt(0)
	ds_write_b128 v24, v[44:47] offset:9216
	ds_write_b128 v24, v[48:51] offset:18432
	v_cmp_gt_i32_e32 vcc, s66, v15
	s_and_saveexec_b64 s[4:5], vcc
	v_cmp_gt_u32_e32 vcc, 8, v15
	s_nop 1
	v_cndmask_b32_e32 v2, 0, v205, vcc
	v_mov_b32_e32 v3, v2
	v_mov_b32_e32 v4, v2
	v_mov_b32_e32 v5, v2
	ds_write_b128 v24, v[2:5] offset:27648
	s_or_b64 exec, exec, s[4:5]
	v_mov_b32_e32 v4, v72
	v_mov_b32_e32 v5, v73
	v_mov_b32_e32 v6, v74
	v_mov_b32_e32 v7, v75
	v_mov_b32_e32 v0, v76
	v_mov_b32_e32 v1, v77
	v_mov_b32_e32 v2, v78
	v_mov_b32_e32 v3, v79
	s_and_saveexec_b64 s[4:5], s[46:47]
	v_lshlrev_b32_e32 v32, 16, v80
	v_and_b32_e32 v33, 0xffff0000, v80
	v_pk_fma_f32 v[4:5], v[84:85], v[32:33], v[4:5]
	v_lshlrev_b32_e32 v34, 16, v81
	v_and_b32_e32 v35, 0xffff0000, v81
	v_pk_fma_f32 v[6:7], v[86:87], v[34:35], v[6:7]
	v_lshlrev_b32_e32 v32, 16, v82
	v_and_b32_e32 v33, 0xffff0000, v82
	v_pk_fma_f32 v[0:1], v[88:89], v[32:33], v[0:1]
	v_lshlrev_b32_e32 v34, 16, v83
	v_and_b32_e32 v35, 0xffff0000, v83
	v_pk_fma_f32 v[2:3], v[90:91], v[34:35], v[2:3]
	s_or_b64 exec, exec, s[4:5]
	s_and_saveexec_b64 s[4:5], s[48:49]
	v_lshlrev_b32_e32 v32, 16, v92
	v_and_b32_e32 v33, 0xffff0000, v92
	v_pk_fma_f32 v[4:5], v[96:97], v[32:33], v[4:5]
	v_lshlrev_b32_e32 v34, 16, v93
	v_and_b32_e32 v35, 0xffff0000, v93
	v_pk_fma_f32 v[6:7], v[98:99], v[34:35], v[6:7]
	v_lshlrev_b32_e32 v32, 16, v94
	v_and_b32_e32 v33, 0xffff0000, v94
	v_pk_fma_f32 v[0:1], v[100:101], v[32:33], v[0:1]
	v_lshlrev_b32_e32 v34, 16, v95
	v_and_b32_e32 v35, 0xffff0000, v95
	v_pk_fma_f32 v[2:3], v[102:103], v[34:35], v[2:3]
	s_or_b64 exec, exec, s[4:5]
	s_and_saveexec_b64 s[4:5], s[50:51]
	v_lshlrev_b32_e32 v32, 16, v104
	v_and_b32_e32 v33, 0xffff0000, v104
	v_pk_fma_f32 v[4:5], v[108:109], v[32:33], v[4:5]
	v_lshlrev_b32_e32 v34, 16, v105
	v_and_b32_e32 v35, 0xffff0000, v105
	v_pk_fma_f32 v[6:7], v[110:111], v[34:35], v[6:7]
	v_lshlrev_b32_e32 v32, 16, v106
	v_and_b32_e32 v33, 0xffff0000, v106
	v_pk_fma_f32 v[0:1], v[112:113], v[32:33], v[0:1]
	v_lshlrev_b32_e32 v34, 16, v107
	v_and_b32_e32 v35, 0xffff0000, v107
	v_pk_fma_f32 v[2:3], v[114:115], v[34:35], v[2:3]
	s_or_b64 exec, exec, s[4:5]
	v_lshlrev_b32_e32 v32, 16, v116
	v_and_b32_e32 v33, 0xffff0000, v116
	v_pk_fma_f32 v[4:5], v[120:121], v[32:33], v[4:5]
	v_lshlrev_b32_e32 v34, 16, v117
	v_and_b32_e32 v35, 0xffff0000, v117
	v_pk_fma_f32 v[6:7], v[122:123], v[34:35], v[6:7]
	v_lshlrev_b32_e32 v32, 16, v118
	v_and_b32_e32 v33, 0xffff0000, v118
	v_pk_fma_f32 v[0:1], v[124:125], v[32:33], v[0:1]
	v_lshlrev_b32_e32 v34, 16, v119
	v_and_b32_e32 v35, 0xffff0000, v119
	v_pk_fma_f32 v[2:3], v[126:127], v[34:35], v[2:3]
	s_waitcnt vmcnt(0)
	v_mul_f32_e32 v11, 0xbfb8aa3b, v4
	v_exp_f32_e32 v11, v11
	s_waitcnt lgkmcnt(0)
	s_barrier
	v_add_f32_e32 v11, 1.0, v11
	v_rcp_f32_e32 v11, v11
	s_movk_i32 s19, 0x7fff
	v_and_b32_e32 v9, 15, v15
	s_lshr_b32 s4, s27, 2
	v_mul_f32_e32 v4, v4, v11
	v_mul_f32_e32 v11, 0xbfb8aa3b, v5
	v_exp_f32_e32 v11, v11
	v_lshrrev_b32_e32 v10, 4, v14
	v_lshlrev_b32_e32 v24, 2, v10
	v_add_f32_e32 v11, 1.0, v11
	v_rcp_f32_e32 v11, v11
	s_nop 0
	v_mul_f32_e32 v5, v5, v11
	v_mul_f32_e32 v11, 0xbfb8aa3b, v6
	v_exp_f32_e32 v11, v11
	s_nop 0
	v_add_f32_e32 v11, 1.0, v11
	v_rcp_f32_e32 v11, v11
	s_nop 0
	v_mul_f32_e32 v6, v6, v11
	v_mul_f32_e32 v11, 0xbfb8aa3b, v7
	v_exp_f32_e32 v11, v11
	s_nop 0
	v_add_f32_e32 v11, 1.0, v11
	v_rcp_f32_e32 v11, v11
	s_nop 0
	v_mul_f32_e32 v7, v7, v11
	v_mul_f32_e32 v11, 0xbfb8aa3b, v0
	v_exp_f32_e32 v11, v11
	s_nop 0
	v_add_f32_e32 v11, 1.0, v11
	v_rcp_f32_e32 v11, v11
	s_nop 0
	v_mul_f32_e32 v0, v0, v11
	v_mul_f32_e32 v11, 0xbfb8aa3b, v1
	v_exp_f32_e32 v11, v11
	s_nop 0
	v_add_f32_e32 v11, 1.0, v11
	v_rcp_f32_e32 v11, v11
	s_nop 0
	v_mul_f32_e32 v1, v1, v11
	v_mul_f32_e32 v11, 0xbfb8aa3b, v2
	v_exp_f32_e32 v11, v11
	s_nop 0
	v_add_f32_e32 v11, 1.0, v11
	v_rcp_f32_e32 v11, v11
	s_nop 0
	v_mul_f32_e32 v2, v2, v11
	v_mul_f32_e32 v11, 0xbfb8aa3b, v3
	v_exp_f32_e32 v11, v11
	s_nop 0
	v_add_f32_e32 v11, 1.0, v11
	v_rcp_f32_e32 v11, v11
	s_nop 0
	v_mul_f32_e32 v3, v3, v11
	v_lshl_add_u32 v11, v8, 2, 0
	ds_read_b32 v12, v11 offset:29952
	v_lshlrev_b32_e32 v8, 1, v8
	v_sub_u32_e32 v8, v11, v8
	v_mad_u32_u24 v8, v16, s84, v8
	s_waitcnt lgkmcnt(0)
	v_mul_f32_e32 v4, v12, v4
	v_bfe_u32 v11, v4, 16, 1
	v_add3_u32 v4, v4, v11, s19
	ds_write_b16_d16_hi v8, v4
	v_mul_f32_e32 v4, v12, v5
	v_bfe_u32 v5, v4, 16, 1
	v_add3_u32 v4, v4, v5, s19
	ds_write_b16_d16_hi v8, v4 offset:144
	v_mul_f32_e32 v4, v12, v6
	v_bfe_u32 v5, v4, 16, 1
	v_add3_u32 v4, v4, v5, s19
	ds_write_b16_d16_hi v8, v4 offset:288
	v_mul_f32_e32 v4, v12, v7
	v_bfe_u32 v5, v4, 16, 1
	v_add3_u32 v4, v4, v5, s19
	v_mul_f32_e32 v0, v12, v0
	ds_write_b16_d16_hi v8, v4 offset:432
	v_bfe_u32 v4, v0, 16, 1
	v_add3_u32 v0, v0, v4, s19
	ds_write_b16_d16_hi v8, v0 offset:576
	v_mul_f32_e32 v0, v12, v1
	v_bfe_u32 v1, v0, 16, 1
	v_add3_u32 v0, v0, v1, s19
	ds_write_b16_d16_hi v8, v0 offset:720
	v_mul_f32_e32 v0, v12, v2
	v_bfe_u32 v1, v0, 16, 1
	v_add3_u32 v0, v0, v1, s19
	ds_write_b16_d16_hi v8, v0 offset:864
	v_mul_f32_e32 v0, v12, v3
	v_bfe_u32 v1, v0, 16, 1
	v_add3_u32 v0, v0, v1, s19
	v_and_or_b32 v11, s4, 48, v9
	s_ashr_i32 s4, s27, 2
	ds_write_b16_d16_hi v8, v0 offset:1008
	v_and_b32_e32 v0, 48, v14
	s_andn2_b32 s4, s4, 63
	v_add_u32_e32 v8, 0, v0
	v_or_b32_e32 v0, s4, v9
	v_mad_u64_u32 v[12:13], s[6:7], v0, s84, v[8:9]
	s_waitcnt lgkmcnt(0)
	s_barrier
	v_mad_u32_u24 v15, v11, s84, v8
	ds_read_b128 v[4:7], v12 offset:9216
	ds_read_b128 v[0:3], v15
	s_waitcnt lgkmcnt(0)
	v_mfma_f32_16x16x32_bf16 v[16:19], v[4:7], v[0:3], 0
	ds_read_b128 v[20:23], v12 offset:9280
	ds_read_b128 v[4:7], v15 offset:64
	v_or_b32_e32 v12, s4, v24
	v_lshl_or_b32 v12, v12, 6, v11
	s_waitcnt lgkmcnt(0)
	v_mfma_f32_16x16x32_bf16 v[16:19], v[20:23], v[4:7], v[16:19]
	s_or_b32 s5, s4, 16
	s_nop 6
	v_bfe_u32 v13, v16, 16, 1
	v_add3_u32 v15, v16, v13, s19
	v_ashrrev_i32_e32 v13, 31, v12
	v_lshl_add_u64 v[12:13], v[12:13], 1, s[16:17]
	global_store_short_d16_hi v[12:13], v15, off
	v_bfe_u32 v15, v17, 16, 1
	v_add3_u32 v15, v17, v15, s19
	global_store_short_d16_hi v[12:13], v15, off offset:128
	v_bfe_u32 v15, v18, 16, 1
	v_add3_u32 v15, v18, v15, s19
	global_store_short_d16_hi v[12:13], v15, off offset:256
	v_bfe_u32 v15, v19, 16, 1
	v_add3_u32 v15, v19, v15, s19
	global_store_short_d16_hi v[12:13], v15, off offset:384
	v_or_b32_e32 v12, s5, v9
	v_mad_u64_u32 v[12:13], s[6:7], v12, s84, v[8:9]
	ds_read_b128 v[16:19], v12 offset:9216
	ds_read_b128 v[20:23], v12 offset:9280
	s_waitcnt lgkmcnt(1)
	v_mfma_f32_16x16x32_bf16 v[16:19], v[16:19], v[0:3], 0
	v_or_b32_e32 v12, s5, v24
	v_lshl_or_b32 v12, v12, 6, v11
	s_or_b32 s5, s4, 32
	s_waitcnt lgkmcnt(0)
	v_mfma_f32_16x16x32_bf16 v[16:19], v[20:23], v[4:7], v[16:19]
	s_nop 7
	v_bfe_u32 v13, v16, 16, 1
	v_add3_u32 v15, v16, v13, s19
	v_ashrrev_i32_e32 v13, 31, v12
	v_lshl_add_u64 v[12:13], v[12:13], 1, s[16:17]
	global_store_short_d16_hi v[12:13], v15, off
	v_bfe_u32 v15, v17, 16, 1
	v_add3_u32 v15, v17, v15, s19
	global_store_short_d16_hi v[12:13], v15, off offset:128
	v_bfe_u32 v15, v18, 16, 1
	v_add3_u32 v15, v18, v15, s19
	global_store_short_d16_hi v[12:13], v15, off offset:256
	v_bfe_u32 v15, v19, 16, 1
	v_add3_u32 v15, v19, v15, s19
	global_store_short_d16_hi v[12:13], v15, off offset:384
	v_or_b32_e32 v12, s5, v9
	v_mad_u64_u32 v[12:13], s[6:7], v12, s84, v[8:9]
	ds_read_b128 v[16:19], v12 offset:9216
	ds_read_b128 v[20:23], v12 offset:9280
	s_waitcnt lgkmcnt(1)
	v_mfma_f32_16x16x32_bf16 v[16:19], v[16:19], v[0:3], 0
	v_or_b32_e32 v12, s5, v24
	v_lshl_or_b32 v12, v12, 6, v11
	s_or_b32 s6, s4, 48
	s_waitcnt lgkmcnt(0)
	v_mfma_f32_16x16x32_bf16 v[16:19], v[20:23], v[4:7], v[16:19]
	s_cmpk_gt_u32 s27, 0xff
	s_nop 6
	v_bfe_u32 v13, v16, 16, 1
	v_add3_u32 v15, v16, v13, s19
	v_ashrrev_i32_e32 v13, 31, v12
	v_lshl_add_u64 v[12:13], v[12:13], 1, s[16:17]
	global_store_short_d16_hi v[12:13], v15, off
	v_bfe_u32 v15, v17, 16, 1
	v_add3_u32 v15, v17, v15, s19
	global_store_short_d16_hi v[12:13], v15, off offset:128
	v_bfe_u32 v15, v18, 16, 1
	v_add3_u32 v15, v18, v15, s19
	global_store_short_d16_hi v[12:13], v15, off offset:256
	v_bfe_u32 v15, v19, 16, 1
	v_add3_u32 v15, v19, v15, s19
	global_store_short_d16_hi v[12:13], v15, off offset:384
	v_or_b32_e32 v12, s6, v9
	v_mad_u64_u32 v[12:13], s[4:5], v12, s84, v[8:9]
	ds_read_b128 v[16:19], v12 offset:9216
	ds_read_b128 v[20:23], v12 offset:9280
	s_waitcnt lgkmcnt(1)
	v_mfma_f32_16x16x32_bf16 v[16:19], v[16:19], v[0:3], 0
	v_or_b32_e32 v8, s6, v24
	s_waitcnt lgkmcnt(0)
	v_mfma_f32_16x16x32_bf16 v[16:19], v[20:23], v[4:7], v[16:19]
	s_nop 7
	v_bfe_u32 v12, v16, 16, 1
	v_add3_u32 v15, v16, v12, s19
	v_lshl_or_b32 v12, v8, 6, v11
	v_ashrrev_i32_e32 v13, 31, v12
	v_bfe_u32 v8, v17, 16, 1
	v_lshl_add_u64 v[12:13], v[12:13], 1, s[16:17]
	v_add3_u32 v8, v17, v8, s19
	global_store_short_d16_hi v[12:13], v8, off offset:128
	v_bfe_u32 v8, v18, 16, 1
	v_add3_u32 v8, v18, v8, s19
	global_store_short_d16_hi v[12:13], v8, off offset:256
	v_bfe_u32 v8, v19, 16, 1
	v_add3_u32 v8, v19, v8, s19
	global_store_short_d16_hi v[12:13], v15, off
	global_store_short_d16_hi v[12:13], v8, off offset:384
	s_cbranch_scc1 .LBB0_287
	v_lshlrev_b32_e32 v8, 3, v10
	v_mul_u32_u24_e32 v9, 0x90, v9
	v_lshlrev_b32_e32 v8, 1, v8
	v_add3_u32 v8, 0, v9, v8
	ds_read_b128 v[16:19], v8 offset:27648
	v_cmp_gt_u32_e32 vcc, 16, v14
	s_waitcnt lgkmcnt(0)
	v_mfma_f32_16x16x32_bf16 v[0:3], v[16:19], v[0:3], 0
	ds_read_b128 v[16:19], v8 offset:27712
	s_waitcnt lgkmcnt(0)
	v_mfma_f32_16x16x32_bf16 v[0:3], v[16:19], v[4:7], v[0:3]
	s_and_saveexec_b64 s[4:5], vcc
	s_cbranch_execz .LBB0_286
	s_nop 5
	v_bfe_u32 v1, v0, 16, 1
	s_movk_i32 s6, 0x7fff
	v_add3_u32 v2, v0, v1, s6
	v_lshlrev_b32_e32 v0, 1, v11
	v_mov_b32_e32 v1, v172
	v_lshl_add_u64 v[0:1], s[16:17], 0, v[0:1]
	v_add_co_u32_e32 v0, vcc, 0x4000, v0
	s_nop 1
	v_addc_co_u32_e32 v1, vcc, 0, v1, vcc
	global_store_short_d16_hi v[0:1], v2, off
	s_branch .LBB0_286
